# in-proj epilogue scale+store passes: stat loads 1..n-1 hoisted behind load 0 into untouched registers, counted vmcnt waits, 8 wait states after each store for the data-VGPR WAR
# speedup vs baseline: 1.0084x; 1.0084x over previous
; __device__ __forceinline__ unsigned cvtpk(float lo, float hi) { f32x2v_ v = {lo, hi}; bf16x2v_ b = __builtin_convertvector(v, bf16x2v_); return __builtin_bit_cast(unsigned, b); }
; __device__ __forceinline__ float row_rs(const float* ssp, int row) { const unsigned long long v = ((const unsigned long long*)ssp)[row];
;     return __builtin_amdgcn_rsqf((float)v * (1.0f / 4294967296.0f) * (1.0f / 1024.0f) + RMS_EPS); }
;     __device__ __forceinline__ void operator()(const f32x4 (&acc)[2][2][4][2], const Unit& u, int wr, int wc, int fr, int fq) const {
;     ...
;             if (cbase < kbeg) {
; #pragma unroll
;                 for (int ai = 0; ai < 2; ++ai)
; #pragma unroll
;                     for (int m = 0; m < 4; ++m) { const int row = row0 + ai * HALF + m * 16; const float rs = ss ? row_rs(ss, row) : 1.0f;
;                         const f32x4 v0 = acc[ai][bj][m][0] * rs, v1 = acc[ai][bj][m][1] * rs;
;                         u32x4 w; w.x = cvtpk(v0[0], v0[1]); w.y = cvtpk(v0[2], v0[3]); w.z = cvtpk(v1[0], v1[1]); w.w = cvtpk(v1[2], v1[3]);
;                         *(u32x4*)(O + (size_t)row * ldc + c0) = w; }
.LBB0_426:
	s_andn2_b64 vcc, exec, s[54:55]
	v_or_b32_e32 v124, 16, v156
	v_or_b32_e32 v122, 32, v156
	v_or_b32_e32 v120, 48, v156
	v_add_u32_e32 v175, 0x80, v156
	v_add_u32_e32 v174, 0x90, v156
	v_add_u32_e32 v173, 0xa0, v156
	v_add_u32_e32 v157, 0xb0, v156
	s_cbranch_vccnz .LBB0_428
	v_ashrrev_i32_e32 v159, 31, v158
	v_cvt_pk_bf16_f32 v164, v164, v165
	v_cvt_pk_bf16_f32 v165, v160, v161
	v_mov_b64_e32 v[160:161], s[20:21]
	v_cvt_pk_bf16_f32 v162, v162, v163
	v_cvt_pk_bf16_f32 v163, v126, v127
	v_mad_i64_i32 v[178:179], s[14:15], v156, s88, v[160:161]
	v_lshlrev_b64 v[126:127], 1, v[158:159]
	v_lshl_add_u64 v[158:159], v[178:179], 0, v[126:127]
	v_ashrrev_i32_e32 v125, 31, v124
	global_store_dwordx4 v[158:159], v[162:165], off
	v_lshl_add_u64 v[158:159], v[124:125], 3, s[24:25]
	global_load_dwordx2 v[158:159], v[158:159], off
	v_or_b32_e32 v182, 32, v156
	v_ashrrev_i32_e32 v183, 31, v182
	v_lshl_add_u64 v[182:183], v[182:183], 3, s[24:25]
	global_load_dwordx2 v[182:183], v[182:183], off
	v_or_b32_e32 v184, 48, v156
	v_ashrrev_i32_e32 v185, 31, v184
	v_lshl_add_u64 v[184:185], v[184:185], 3, s[24:25]
	global_load_dwordx2 v[184:185], v[184:185], off
	global_load_dwordx2 v[186:187], v[154:155], off offset:1024
	global_load_dwordx2 v[188:189], v[154:155], off offset:1152
	global_load_dwordx2 v[190:191], v[154:155], off offset:1280
	global_load_dwordx2 v[192:193], v[154:155], off offset:1408
	s_waitcnt vmcnt(6)
	v_ffbh_u32_e32 v121, v159
	v_min_u32_e32 v121, 32, v121
	v_lshlrev_b64 v[158:159], v121, v[158:159]
	v_min_u32_e32 v123, 1, v158
	v_or_b32_e32 v123, v159, v123
	v_cvt_f32_u32_e32 v125, v123
	v_sub_u32_e32 v121, 32, v121
	v_mad_i64_i32 v[158:159], s[14:15], v124, s88, v[160:161]
	v_ldexp_f32 v121, v125, v121
	v_mul_f32_e32 v121, 0x2f800000, v121
	v_fmamk_f32 v121, v121, 0x3a800000, v172
	v_rsq_f32_e32 v136, v121
	v_ashrrev_i32_e32 v123, 31, v122
	v_lshl_add_u64 v[158:159], v[158:159], 0, v[126:127]
	v_lshl_add_u64 v[162:163], v[122:123], 3, s[24:25]
	v_pk_mul_f32 v[118:119], v[118:119], v[136:137] op_sel_hi:[1,0]
	v_pk_mul_f32 v[116:117], v[116:117], v[136:137] op_sel_hi:[1,0]
	v_pk_mul_f32 v[164:165], v[114:115], v[136:137] op_sel_hi:[1,0]
	v_pk_mul_f32 v[114:115], v[112:113], v[136:137] op_sel_hi:[1,0]
	v_cvt_pk_bf16_f32 v112, v116, v117
	v_cvt_pk_bf16_f32 v113, v118, v119
	v_cvt_pk_bf16_f32 v114, v114, v115
	v_cvt_pk_bf16_f32 v115, v164, v165
	global_store_dwordx4 v[158:159], v[112:115], off
	s_nop 7
	v_ashrrev_i32_e32 v121, 31, v120
	v_lshl_add_u64 v[116:117], v[120:121], 3, s[24:25]
	s_waitcnt vmcnt(6)
	v_ffbh_u32_e32 v114, v183
	v_min_u32_e32 v114, 32, v114
	v_lshlrev_b64 v[112:113], v114, v[182:183]
	v_min_u32_e32 v112, 1, v112
	v_or_b32_e32 v112, v113, v112
	v_cvt_f32_u32_e32 v112, v112
	v_sub_u32_e32 v113, 32, v114
	v_mad_i64_i32 v[114:115], s[14:15], v122, s88, v[160:161]
	v_ldexp_f32 v112, v112, v113
	v_mul_f32_e32 v112, 0x2f800000, v112
	v_fmamk_f32 v112, v112, 0x3a800000, v172
	v_rsq_f32_e32 v112, v112
	v_lshl_add_u64 v[114:115], v[114:115], 0, v[126:127]
	v_pk_mul_f32 v[110:111], v[110:111], v[112:113] op_sel_hi:[1,0]
	v_pk_mul_f32 v[108:109], v[108:109], v[112:113] op_sel_hi:[1,0]
	v_pk_mul_f32 v[118:119], v[106:107], v[112:113] op_sel_hi:[1,0]
	v_pk_mul_f32 v[106:107], v[104:105], v[112:113] op_sel_hi:[1,0]
	v_cvt_pk_bf16_f32 v104, v108, v109
	v_cvt_pk_bf16_f32 v105, v110, v111
	v_cvt_pk_bf16_f32 v106, v106, v107
	v_cvt_pk_bf16_f32 v107, v118, v119
	global_store_dwordx4 v[114:115], v[104:107], off
	s_nop 7
	s_waitcnt vmcnt(6)
	v_ffbh_u32_e32 v106, v185
	v_min_u32_e32 v106, 32, v106
	v_lshlrev_b64 v[104:105], v106, v[184:185]
	v_min_u32_e32 v104, 1, v104
	v_or_b32_e32 v104, v105, v104
	v_cvt_f32_u32_e32 v104, v104
	v_sub_u32_e32 v105, 32, v106
	v_mad_i64_i32 v[106:107], s[14:15], v120, s88, v[160:161]
	v_ldexp_f32 v104, v104, v105
	v_mul_f32_e32 v104, 0x2f800000, v104
	v_fmamk_f32 v104, v104, 0x3a800000, v172
	v_rsq_f32_e32 v104, v104
	v_lshl_add_u64 v[106:107], v[106:107], 0, v[126:127]
	v_pk_mul_f32 v[102:103], v[102:103], v[104:105] op_sel_hi:[1,0]
	v_pk_mul_f32 v[100:101], v[100:101], v[104:105] op_sel_hi:[1,0]
	v_pk_mul_f32 v[108:109], v[98:99], v[104:105] op_sel_hi:[1,0]
	v_pk_mul_f32 v[98:99], v[96:97], v[104:105] op_sel_hi:[1,0]
	v_cvt_pk_bf16_f32 v96, v100, v101
	v_cvt_pk_bf16_f32 v97, v102, v103
	v_cvt_pk_bf16_f32 v98, v98, v99
	v_cvt_pk_bf16_f32 v99, v108, v109
	global_store_dwordx4 v[106:107], v[96:99], off
	s_nop 7
	s_waitcnt vmcnt(6)
; __device__ __forceinline__ unsigned cvtpk(float lo, float hi) { f32x2v_ v = {lo, hi}; bf16x2v_ b = __builtin_convertvector(v, bf16x2v_); return __builtin_bit_cast(unsigned, b); }
; __device__ __forceinline__ float row_rs(const float* ssp, int row) { const unsigned long long v = ((const unsigned long long*)ssp)[row];
;     return __builtin_amdgcn_rsqf((float)v * (1.0f / 4294967296.0f) * (1.0f / 1024.0f) + RMS_EPS); }
;     __device__ __forceinline__ void operator()(const f32x4 (&acc)[2][2][4][2], const Unit& u, int wr, int wc, int fr, int fq) const {
;     ...
;                     for (int m = 0; m < 4; ++m) { const int row = row0 + ai * HALF + m * 16; const float rs = ss ? row_rs(ss, row) : 1.0f;
;                         const f32x4 v0 = acc[ai][bj][m][0] * rs, v1 = acc[ai][bj][m][1] * rs;
;                         u32x4 w; w.x = cvtpk(v0[0], v0[1]); w.y = cvtpk(v0[2], v0[3]); w.z = cvtpk(v1[0], v1[1]); w.w = cvtpk(v1[2], v1[3]);
;                         *(u32x4*)(O + (size_t)row * ldc + c0) = w; }
	v_ffbh_u32_e32 v98, v187
	v_min_u32_e32 v98, 32, v98
	v_lshlrev_b64 v[96:97], v98, v[186:187]
	v_min_u32_e32 v96, 1, v96
	v_or_b32_e32 v96, v97, v96
	v_cvt_f32_u32_e32 v96, v96
	v_sub_u32_e32 v97, 32, v98
	v_mad_i64_i32 v[98:99], s[14:15], v175, s88, v[160:161]
	v_ldexp_f32 v96, v96, v97
	v_mul_f32_e32 v96, 0x2f800000, v96
	v_fmamk_f32 v96, v96, 0x3a800000, v172
	v_rsq_f32_e32 v96, v96
	v_lshl_add_u64 v[98:99], v[98:99], 0, v[126:127]
	v_pk_mul_f32 v[94:95], v[94:95], v[96:97] op_sel_hi:[1,0]
	v_pk_mul_f32 v[92:93], v[92:93], v[96:97] op_sel_hi:[1,0]
	v_pk_mul_f32 v[100:101], v[90:91], v[96:97] op_sel_hi:[1,0]
	v_pk_mul_f32 v[90:91], v[88:89], v[96:97] op_sel_hi:[1,0]
	v_cvt_pk_bf16_f32 v88, v92, v93
	v_cvt_pk_bf16_f32 v89, v94, v95
	v_cvt_pk_bf16_f32 v90, v90, v91
	v_cvt_pk_bf16_f32 v91, v100, v101
	global_store_dwordx4 v[98:99], v[88:91], off
	s_nop 7
	s_waitcnt vmcnt(6)
	v_ffbh_u32_e32 v90, v189
	v_min_u32_e32 v90, 32, v90
	v_lshlrev_b64 v[88:89], v90, v[188:189]
	v_min_u32_e32 v88, 1, v88
	v_or_b32_e32 v88, v89, v88
	v_cvt_f32_u32_e32 v88, v88
	v_sub_u32_e32 v89, 32, v90
	v_mad_i64_i32 v[90:91], s[14:15], v174, s88, v[160:161]
	v_ldexp_f32 v88, v88, v89
	v_mul_f32_e32 v88, 0x2f800000, v88
	v_fmamk_f32 v88, v88, 0x3a800000, v172
	v_rsq_f32_e32 v88, v88
	v_lshl_add_u64 v[90:91], v[90:91], 0, v[126:127]
	v_pk_mul_f32 v[86:87], v[86:87], v[88:89] op_sel_hi:[1,0]
	v_pk_mul_f32 v[84:85], v[84:85], v[88:89] op_sel_hi:[1,0]
	v_pk_mul_f32 v[92:93], v[82:83], v[88:89] op_sel_hi:[1,0]
	v_pk_mul_f32 v[82:83], v[80:81], v[88:89] op_sel_hi:[1,0]
	v_cvt_pk_bf16_f32 v80, v84, v85
	v_cvt_pk_bf16_f32 v81, v86, v87
	v_cvt_pk_bf16_f32 v82, v82, v83
	v_cvt_pk_bf16_f32 v83, v92, v93
	global_store_dwordx4 v[90:91], v[80:83], off
	s_nop 7
	s_waitcnt vmcnt(6)
	v_ffbh_u32_e32 v82, v191
	v_min_u32_e32 v82, 32, v82
	v_lshlrev_b64 v[80:81], v82, v[190:191]
	v_min_u32_e32 v80, 1, v80
	v_or_b32_e32 v80, v81, v80
	v_cvt_f32_u32_e32 v80, v80
	v_sub_u32_e32 v81, 32, v82
	v_mad_i64_i32 v[82:83], s[14:15], v173, s88, v[160:161]
	v_ldexp_f32 v80, v80, v81
	v_mul_f32_e32 v80, 0x2f800000, v80
	v_fmamk_f32 v80, v80, 0x3a800000, v172
	v_rsq_f32_e32 v80, v80
	v_lshl_add_u64 v[82:83], v[82:83], 0, v[126:127]
	v_pk_mul_f32 v[78:79], v[78:79], v[80:81] op_sel_hi:[1,0]
	v_pk_mul_f32 v[76:77], v[76:77], v[80:81] op_sel_hi:[1,0]
	v_pk_mul_f32 v[84:85], v[74:75], v[80:81] op_sel_hi:[1,0]
	v_pk_mul_f32 v[74:75], v[72:73], v[80:81] op_sel_hi:[1,0]
	v_cvt_pk_bf16_f32 v72, v76, v77
	v_cvt_pk_bf16_f32 v73, v78, v79
	v_cvt_pk_bf16_f32 v74, v74, v75
	v_cvt_pk_bf16_f32 v75, v84, v85
	global_store_dwordx4 v[82:83], v[72:75], off
	s_nop 7
	s_waitcnt vmcnt(6)
	v_ffbh_u32_e32 v74, v193
	v_min_u32_e32 v74, 32, v74
	v_lshlrev_b64 v[72:73], v74, v[192:193]
	v_min_u32_e32 v72, 1, v72
	v_or_b32_e32 v72, v73, v72
	v_cvt_f32_u32_e32 v72, v72
	v_sub_u32_e32 v73, 32, v74
	v_mad_i64_i32 v[74:75], s[14:15], v157, s88, v[160:161]
	v_ldexp_f32 v72, v72, v73
	v_mul_f32_e32 v72, 0x2f800000, v72
	v_fmamk_f32 v72, v72, 0x3a800000, v172
	v_rsq_f32_e32 v72, v72
	s_nop 0
	v_pk_mul_f32 v[62:63], v[62:63], v[72:73] op_sel_hi:[1,0]
	v_pk_mul_f32 v[60:61], v[60:61], v[72:73] op_sel_hi:[1,0]
	v_pk_mul_f32 v[76:77], v[58:59], v[72:73] op_sel_hi:[1,0]
	v_pk_mul_f32 v[58:59], v[56:57], v[72:73] op_sel_hi:[1,0]
	v_cvt_pk_bf16_f32 v56, v60, v61
	v_cvt_pk_bf16_f32 v57, v62, v63
	v_cvt_pk_bf16_f32 v58, v58, v59
	v_cvt_pk_bf16_f32 v59, v76, v77
	v_lshl_add_u64 v[60:61], v[74:75], 0, v[126:127]
	global_store_dwordx4 v[60:61], v[56:59], off
	s_nop 7

; __device__ __forceinline__ unsigned cvtpk(float lo, float hi) { f32x2v_ v = {lo, hi}; bf16x2v_ b = __builtin_convertvector(v, bf16x2v_); return __builtin_bit_cast(unsigned, b); }
; __device__ __forceinline__ float row_rs(const float* ssp, int row) { const unsigned long long v = ((const unsigned long long*)ssp)[row];
;     return __builtin_amdgcn_rsqf((float)v * (1.0f / 4294967296.0f) * (1.0f / 1024.0f) + RMS_EPS); }
;     __device__ __forceinline__ void operator()(const f32x4 (&acc)[2][2][4][2], const Unit& u, int wr, int wc, int fr, int fq) const {
;     ...
;             if (cbase < kbeg) {
; #pragma unroll
;                 for (int ai = 0; ai < 2; ++ai)
; #pragma unroll
;                     for (int m = 0; m < 4; ++m) { const int row = row0 + ai * HALF + m * 16; const float rs = ss ? row_rs(ss, row) : 1.0f;
;                         const f32x4 v0 = acc[ai][bj][m][0] * rs, v1 = acc[ai][bj][m][1] * rs;
;                         u32x4 w; w.x = cvtpk(v0[0], v0[1]); w.y = cvtpk(v0[2], v0[3]); w.z = cvtpk(v1[0], v1[1]); w.w = cvtpk(v1[2], v1[3]);
;                         *(u32x4*)(O + (size_t)row * ldc + c0) = w; }
.LBB0_436:
	s_ashr_i32 s53, s52, 31
	v_cvt_pk_bf16_f32 v64, v58, v59
	v_cvt_pk_bf16_f32 v65, v56, v57
	v_mov_b64_e32 v[58:59], s[20:21]
	v_lshl_add_u64 v[56:57], s[52:53], 0, v[138:139]
	v_cvt_pk_bf16_f32 v67, v60, v61
	v_mad_i64_i32 v[60:61], s[14:15], v156, s88, v[58:59]
	v_lshlrev_b64 v[56:57], 1, v[56:57]
	v_cvt_pk_bf16_f32 v66, v62, v63
	v_lshl_add_u64 v[60:61], v[60:61], 0, v[56:57]
	v_ashrrev_i32_e32 v125, 31, v124
	global_store_dwordx4 v[60:61], v[64:67], off offset:256
	v_lshl_add_u64 v[60:61], v[124:125], 3, s[24:25]
	global_load_dwordx2 v[60:61], v[60:61], off
	v_mov_b32_e32 v68, v122
	v_ashrrev_i32_e32 v69, 31, v68
	v_lshl_add_u64 v[68:69], v[68:69], 3, s[24:25]
	global_load_dwordx2 v[68:69], v[68:69], off
	v_mov_b32_e32 v70, v120
	v_ashrrev_i32_e32 v71, 31, v70
	v_lshl_add_u64 v[70:71], v[70:71], 3, s[24:25]
	global_load_dwordx2 v[70:71], v[70:71], off
	global_load_dwordx2 v[72:73], v[154:155], off offset:1024
	global_load_dwordx2 v[74:75], v[154:155], off offset:1152
	global_load_dwordx2 v[76:77], v[154:155], off offset:1280
	global_load_dwordx2 v[78:79], v[154:155], off offset:1408
	v_ashrrev_i32_e32 v123, 31, v122
	v_lshl_add_u64 v[64:65], v[122:123], 3, s[24:25]
	v_ashrrev_i32_e32 v121, 31, v120
	s_waitcnt vmcnt(6)
	v_ffbh_u32_e32 v62, v61
	v_min_u32_e32 v62, 32, v62
	v_lshlrev_b64 v[60:61], v62, v[60:61]
	v_min_u32_e32 v60, 1, v60
	v_or_b32_e32 v60, v61, v60
	v_cvt_f32_u32_e32 v60, v60
	v_sub_u32_e32 v61, 32, v62
	v_mad_i64_i32 v[62:63], s[14:15], v124, s88, v[58:59]
	v_ldexp_f32 v60, v60, v61
	v_mul_f32_e32 v60, 0x2f800000, v60
	v_fmamk_f32 v60, v60, 0x3a800000, v172
	v_rsq_f32_e32 v60, v60
	v_lshl_add_u64 v[62:63], v[62:63], 0, v[56:57]
	v_pk_mul_f32 v[54:55], v[54:55], v[60:61] op_sel_hi:[1,0]
	v_pk_mul_f32 v[52:53], v[52:53], v[60:61] op_sel_hi:[1,0]
	v_pk_mul_f32 v[66:67], v[50:51], v[60:61] op_sel_hi:[1,0]
	v_pk_mul_f32 v[50:51], v[48:49], v[60:61] op_sel_hi:[1,0]
	v_cvt_pk_bf16_f32 v48, v52, v53
	v_cvt_pk_bf16_f32 v49, v54, v55
	v_cvt_pk_bf16_f32 v50, v50, v51
	v_cvt_pk_bf16_f32 v51, v66, v67
	global_store_dwordx4 v[62:63], v[48:51], off offset:256
	s_nop 7
	v_lshl_add_u64 v[52:53], v[120:121], 3, s[24:25]
	s_waitcnt vmcnt(6)
	v_ffbh_u32_e32 v50, v69
	v_min_u32_e32 v50, 32, v50
	v_lshlrev_b64 v[48:49], v50, v[68:69]
	v_min_u32_e32 v48, 1, v48
	v_or_b32_e32 v48, v49, v48
	v_cvt_f32_u32_e32 v48, v48
	v_sub_u32_e32 v49, 32, v50
	v_mad_i64_i32 v[50:51], s[14:15], v122, s88, v[58:59]
	v_ldexp_f32 v48, v48, v49
	v_mul_f32_e32 v48, 0x2f800000, v48
	v_fmamk_f32 v48, v48, 0x3a800000, v172
	v_rsq_f32_e32 v48, v48
	v_lshl_add_u64 v[50:51], v[50:51], 0, v[56:57]
	v_pk_mul_f32 v[46:47], v[46:47], v[48:49] op_sel_hi:[1,0]
	v_pk_mul_f32 v[44:45], v[44:45], v[48:49] op_sel_hi:[1,0]
	v_pk_mul_f32 v[54:55], v[42:43], v[48:49] op_sel_hi:[1,0]
	v_pk_mul_f32 v[42:43], v[40:41], v[48:49] op_sel_hi:[1,0]
	v_cvt_pk_bf16_f32 v40, v44, v45
	v_cvt_pk_bf16_f32 v41, v46, v47
	v_cvt_pk_bf16_f32 v42, v42, v43
	v_cvt_pk_bf16_f32 v43, v54, v55
	global_store_dwordx4 v[50:51], v[40:43], off offset:256
	s_nop 7
	s_waitcnt vmcnt(6)
	v_ffbh_u32_e32 v42, v71
	v_min_u32_e32 v42, 32, v42
	v_lshlrev_b64 v[40:41], v42, v[70:71]
	v_min_u32_e32 v40, 1, v40
	v_or_b32_e32 v40, v41, v40
	v_cvt_f32_u32_e32 v40, v40
	v_sub_u32_e32 v41, 32, v42
	v_mad_i64_i32 v[42:43], s[14:15], v120, s88, v[58:59]
	v_ldexp_f32 v40, v40, v41
	v_mul_f32_e32 v40, 0x2f800000, v40
	v_fmamk_f32 v40, v40, 0x3a800000, v172
	v_rsq_f32_e32 v40, v40
	v_lshl_add_u64 v[42:43], v[42:43], 0, v[56:57]
	v_pk_mul_f32 v[38:39], v[38:39], v[40:41] op_sel_hi:[1,0]
	v_pk_mul_f32 v[36:37], v[36:37], v[40:41] op_sel_hi:[1,0]
	v_pk_mul_f32 v[44:45], v[34:35], v[40:41] op_sel_hi:[1,0]
	v_pk_mul_f32 v[34:35], v[32:33], v[40:41] op_sel_hi:[1,0]
	v_cvt_pk_bf16_f32 v32, v36, v37
	v_cvt_pk_bf16_f32 v33, v38, v39
	v_cvt_pk_bf16_f32 v34, v34, v35
	v_cvt_pk_bf16_f32 v35, v44, v45
	global_store_dwordx4 v[42:43], v[32:35], off offset:256
	s_nop 7
	s_waitcnt vmcnt(6)
; __device__ __forceinline__ unsigned cvtpk(float lo, float hi) { f32x2v_ v = {lo, hi}; bf16x2v_ b = __builtin_convertvector(v, bf16x2v_); return __builtin_bit_cast(unsigned, b); }
; __device__ __forceinline__ float row_rs(const float* ssp, int row) { const unsigned long long v = ((const unsigned long long*)ssp)[row];
;     return __builtin_amdgcn_rsqf((float)v * (1.0f / 4294967296.0f) * (1.0f / 1024.0f) + RMS_EPS); }
;     __device__ __forceinline__ void operator()(const f32x4 (&acc)[2][2][4][2], const Unit& u, int wr, int wc, int fr, int fq) const {
;     ...
;                     for (int m = 0; m < 4; ++m) { const int row = row0 + ai * HALF + m * 16; const float rs = ss ? row_rs(ss, row) : 1.0f;
;                         const f32x4 v0 = acc[ai][bj][m][0] * rs, v1 = acc[ai][bj][m][1] * rs;
;                         u32x4 w; w.x = cvtpk(v0[0], v0[1]); w.y = cvtpk(v0[2], v0[3]); w.z = cvtpk(v1[0], v1[1]); w.w = cvtpk(v1[2], v1[3]);
;                         *(u32x4*)(O + (size_t)row * ldc + c0) = w; }
	v_ffbh_u32_e32 v34, v73
	v_min_u32_e32 v34, 32, v34
	v_lshlrev_b64 v[32:33], v34, v[72:73]
	v_min_u32_e32 v32, 1, v32
	v_or_b32_e32 v32, v33, v32
	v_cvt_f32_u32_e32 v32, v32
	v_sub_u32_e32 v33, 32, v34
	v_mad_i64_i32 v[34:35], s[14:15], v175, s88, v[58:59]
	v_ldexp_f32 v32, v32, v33
	v_mul_f32_e32 v32, 0x2f800000, v32
	v_fmamk_f32 v32, v32, 0x3a800000, v172
	v_rsq_f32_e32 v32, v32
	v_lshl_add_u64 v[34:35], v[34:35], 0, v[56:57]
	v_pk_mul_f32 v[30:31], v[30:31], v[32:33] op_sel_hi:[1,0]
	v_pk_mul_f32 v[28:29], v[28:29], v[32:33] op_sel_hi:[1,0]
	v_pk_mul_f32 v[36:37], v[26:27], v[32:33] op_sel_hi:[1,0]
	v_pk_mul_f32 v[26:27], v[24:25], v[32:33] op_sel_hi:[1,0]
	v_cvt_pk_bf16_f32 v24, v28, v29
	v_cvt_pk_bf16_f32 v25, v30, v31
	v_cvt_pk_bf16_f32 v26, v26, v27
	v_cvt_pk_bf16_f32 v27, v36, v37
	global_store_dwordx4 v[34:35], v[24:27], off offset:256
	s_nop 7
	s_waitcnt vmcnt(6)
	v_ffbh_u32_e32 v26, v75
	v_min_u32_e32 v26, 32, v26
	v_lshlrev_b64 v[24:25], v26, v[74:75]
	v_min_u32_e32 v24, 1, v24
	v_or_b32_e32 v24, v25, v24
	v_cvt_f32_u32_e32 v24, v24
	v_sub_u32_e32 v25, 32, v26
	v_mad_i64_i32 v[26:27], s[14:15], v174, s88, v[58:59]
	v_ldexp_f32 v24, v24, v25
	v_mul_f32_e32 v24, 0x2f800000, v24
	v_fmamk_f32 v24, v24, 0x3a800000, v172
	v_rsq_f32_e32 v24, v24
	v_lshl_add_u64 v[26:27], v[26:27], 0, v[56:57]
	v_pk_mul_f32 v[22:23], v[22:23], v[24:25] op_sel_hi:[1,0]
	v_pk_mul_f32 v[20:21], v[20:21], v[24:25] op_sel_hi:[1,0]
	v_pk_mul_f32 v[28:29], v[18:19], v[24:25] op_sel_hi:[1,0]
	v_pk_mul_f32 v[18:19], v[16:17], v[24:25] op_sel_hi:[1,0]
	v_cvt_pk_bf16_f32 v16, v20, v21
	v_cvt_pk_bf16_f32 v17, v22, v23
	v_cvt_pk_bf16_f32 v18, v18, v19
	v_cvt_pk_bf16_f32 v19, v28, v29
	global_store_dwordx4 v[26:27], v[16:19], off offset:256
	s_nop 7
	s_waitcnt vmcnt(6)
	v_ffbh_u32_e32 v18, v77
	v_min_u32_e32 v18, 32, v18
	v_lshlrev_b64 v[16:17], v18, v[76:77]
	v_min_u32_e32 v16, 1, v16
	v_or_b32_e32 v16, v17, v16
	v_cvt_f32_u32_e32 v16, v16
	v_sub_u32_e32 v17, 32, v18
	v_mad_i64_i32 v[18:19], s[14:15], v173, s88, v[58:59]
	v_ldexp_f32 v16, v16, v17
	v_mul_f32_e32 v16, 0x2f800000, v16
	v_fmamk_f32 v16, v16, 0x3a800000, v172
	v_rsq_f32_e32 v16, v16
	v_lshl_add_u64 v[18:19], v[18:19], 0, v[56:57]
	v_pk_mul_f32 v[14:15], v[14:15], v[16:17] op_sel_hi:[1,0]
	v_pk_mul_f32 v[12:13], v[12:13], v[16:17] op_sel_hi:[1,0]
	v_pk_mul_f32 v[20:21], v[10:11], v[16:17] op_sel_hi:[1,0]
	v_pk_mul_f32 v[10:11], v[8:9], v[16:17] op_sel_hi:[1,0]
	v_cvt_pk_bf16_f32 v8, v12, v13
	v_cvt_pk_bf16_f32 v9, v14, v15
	v_cvt_pk_bf16_f32 v10, v10, v11
	v_cvt_pk_bf16_f32 v11, v20, v21
	global_store_dwordx4 v[18:19], v[8:11], off offset:256
	s_nop 7
	s_waitcnt vmcnt(6)
	v_ffbh_u32_e32 v10, v79
	v_min_u32_e32 v10, 32, v10
	v_lshlrev_b64 v[8:9], v10, v[78:79]
	v_min_u32_e32 v8, 1, v8
	v_or_b32_e32 v8, v9, v8
	v_cvt_f32_u32_e32 v8, v8
	v_sub_u32_e32 v9, 32, v10
	v_mad_i64_i32 v[10:11], s[14:15], v157, s88, v[58:59]
	v_ldexp_f32 v8, v8, v9
	v_mul_f32_e32 v8, 0x2f800000, v8
	v_fmamk_f32 v8, v8, 0x3a800000, v172
	v_rsq_f32_e32 v8, v8
	s_nop 0
	v_pk_mul_f32 v[6:7], v[6:7], v[8:9] op_sel_hi:[1,0]
	v_pk_mul_f32 v[4:5], v[4:5], v[8:9] op_sel_hi:[1,0]
	v_pk_mul_f32 v[12:13], v[2:3], v[8:9] op_sel_hi:[1,0]
	v_pk_mul_f32 v[2:3], v[0:1], v[8:9] op_sel_hi:[1,0]
	v_cvt_pk_bf16_f32 v0, v4, v5
	v_cvt_pk_bf16_f32 v1, v6, v7
	v_cvt_pk_bf16_f32 v2, v2, v3
	v_cvt_pk_bf16_f32 v3, v12, v13
	v_lshl_add_u64 v[4:5], v[10:11], 0, v[56:57]
	global_store_dwordx4 v[4:5], v[0:3], off offset:256
	s_nop 7
	s_andn2_b64 vcc, exec, s[6:7]
	s_mov_b64 s[6:7], -1
	s_cbranch_vccnz .LBB0_413

; __device__ __forceinline__ unsigned cvtpk(float lo, float hi) { f32x2v_ v = {lo, hi}; bf16x2v_ b = __builtin_convertvector(v, bf16x2v_); return __builtin_bit_cast(unsigned, b); }
; __device__ __forceinline__ float row_rs(const float* ssp, int row) { const unsigned long long v = ((const unsigned long long*)ssp)[row];
;     return __builtin_amdgcn_rsqf((float)v * (1.0f / 4294967296.0f) * (1.0f / 1024.0f) + RMS_EPS); }
;     __device__ __forceinline__ void operator()(const f32x4 (&acc)[2][2][4][2], const Unit& u, int wr, int wc, int fr, int fq) const {
;     ...
;             if (cbase < kbeg) {
; #pragma unroll
;                 for (int ai = 0; ai < 2; ++ai)
; #pragma unroll
;                     for (int m = 0; m < 4; ++m) { const int row = row0 + ai * HALF + m * 16; const float rs = ss ? row_rs(ss, row) : 1.0f;
;                         const f32x4 v0 = acc[ai][bj][m][0] * rs, v1 = acc[ai][bj][m][1] * rs;
;                         u32x4 w; w.x = cvtpk(v0[0], v0[1]); w.y = cvtpk(v0[2], v0[3]); w.z = cvtpk(v1[0], v1[1]); w.w = cvtpk(v1[2], v1[3]);
;                         *(u32x4*)(O + (size_t)row * ldc + c0) = w; }
.LBB0_1302:
	v_lshl_add_u64 v[164:165], v[160:161], 3, s[36:37]
	global_load_dwordx2 v[166:167], v[164:165], off
	v_mov_b32_e32 v182, v162
	v_ashrrev_i32_e32 v183, 31, v182
	v_lshl_add_u64 v[182:183], v[182:183], 3, s[36:37]
	global_load_dwordx2 v[182:183], v[182:183], off
	v_mov_b32_e32 v184, v130
	v_ashrrev_i32_e32 v185, 31, v184
	v_lshl_add_u64 v[184:185], v[184:185], 3, s[36:37]
	global_load_dwordx2 v[184:185], v[184:185], off
	v_mov_b32_e32 v186, v128
	v_ashrrev_i32_e32 v187, 31, v186
	v_lshl_add_u64 v[186:187], v[186:187], 3, s[36:37]
	global_load_dwordx2 v[186:187], v[186:187], off
	global_load_dwordx2 v[188:189], v[164:165], off offset:1024
	global_load_dwordx2 v[190:191], v[164:165], off offset:1152
	global_load_dwordx2 v[192:193], v[164:165], off offset:1280
	global_load_dwordx2 v[194:195], v[164:165], off offset:1408
	v_or_b32_e32 v168, s58, v142
	v_lshlrev_b64 v[170:171], 12, v[160:161]
	v_ashrrev_i32_e32 v169, 31, v168
	v_lshlrev_b64 v[168:169], 1, v[168:169]
	v_lshl_add_u64 v[172:173], v[162:163], 3, s[36:37]
	s_waitcnt vmcnt(7)
	v_ffbh_u32_e32 v140, v167
	v_min_u32_e32 v140, 32, v140
	v_lshlrev_b64 v[166:167], v140, v[166:167]
	v_min_u32_e32 v166, 1, v166
	v_or_b32_e32 v166, v167, v166
	v_cvt_f32_u32_e32 v166, v166
	v_sub_u32_e32 v140, 32, v140
	v_ldexp_f32 v140, v166, v140
	v_mul_f32_e32 v140, 0x2f800000, v140
	v_fmamk_f32 v140, v140, 0x3a800000, v209
	v_rsq_f32_e32 v140, v140
	v_lshl_add_u64 v[166:167], s[20:21], 0, v[170:171]
	v_lshl_add_u64 v[166:167], v[166:167], 0, v[168:169]
	v_pk_mul_f32 v[126:127], v[126:127], v[140:141] op_sel_hi:[1,0]
	v_pk_mul_f32 v[124:125], v[124:125], v[140:141] op_sel_hi:[1,0]
	v_pk_mul_f32 v[170:171], v[122:123], v[140:141] op_sel_hi:[1,0]
	v_pk_mul_f32 v[122:123], v[120:121], v[140:141] op_sel_hi:[1,0]
	v_cvt_pk_bf16_f32 v120, v124, v125
	v_cvt_pk_bf16_f32 v121, v126, v127
	v_cvt_pk_bf16_f32 v122, v122, v123
	v_cvt_pk_bf16_f32 v123, v170, v171
	global_store_dwordx4 v[166:167], v[120:123], off
	s_nop 7
	v_lshl_add_u64 v[124:125], v[130:131], 3, s[36:37]
	s_waitcnt vmcnt(7)
	v_ffbh_u32_e32 v122, v183
	v_min_u32_e32 v122, 32, v122
	v_lshlrev_b64 v[120:121], v122, v[182:183]
	v_min_u32_e32 v120, 1, v120
	v_or_b32_e32 v120, v121, v120
	v_cvt_f32_u32_e32 v123, v120
	v_sub_u32_e32 v122, 32, v122
	v_lshlrev_b64 v[120:121], 12, v[162:163]
	v_lshl_add_u64 v[120:121], s[20:21], 0, v[120:121]
	v_ldexp_f32 v122, v123, v122
	v_mul_f32_e32 v122, 0x2f800000, v122
	v_fmamk_f32 v122, v122, 0x3a800000, v209
	v_rsq_f32_e32 v122, v122
	v_lshl_add_u64 v[120:121], v[120:121], 0, v[168:169]
	v_pk_mul_f32 v[118:119], v[118:119], v[122:123] op_sel_hi:[1,0]
	v_pk_mul_f32 v[116:117], v[116:117], v[122:123] op_sel_hi:[1,0]
	v_pk_mul_f32 v[126:127], v[114:115], v[122:123] op_sel_hi:[1,0]
	v_pk_mul_f32 v[114:115], v[112:113], v[122:123] op_sel_hi:[1,0]
	v_cvt_pk_bf16_f32 v112, v116, v117
	v_cvt_pk_bf16_f32 v113, v118, v119
	v_cvt_pk_bf16_f32 v114, v114, v115
	v_cvt_pk_bf16_f32 v115, v126, v127
	global_store_dwordx4 v[120:121], v[112:115], off
	s_nop 7
	v_lshl_add_u64 v[116:117], v[128:129], 3, s[36:37]
	s_waitcnt vmcnt(7)
	v_ffbh_u32_e32 v114, v185
	v_min_u32_e32 v114, 32, v114
	v_lshlrev_b64 v[112:113], v114, v[184:185]
	v_min_u32_e32 v112, 1, v112
	v_or_b32_e32 v112, v113, v112
	v_cvt_f32_u32_e32 v115, v112
	v_sub_u32_e32 v114, 32, v114
	v_lshlrev_b64 v[112:113], 12, v[130:131]
	v_lshl_add_u64 v[112:113], s[20:21], 0, v[112:113]
	v_ldexp_f32 v114, v115, v114
	v_mul_f32_e32 v114, 0x2f800000, v114
	v_fmamk_f32 v114, v114, 0x3a800000, v209
	v_rsq_f32_e32 v114, v114
	v_lshl_add_u64 v[112:113], v[112:113], 0, v[168:169]
	v_pk_mul_f32 v[110:111], v[110:111], v[114:115] op_sel_hi:[1,0]
	v_pk_mul_f32 v[108:109], v[108:109], v[114:115] op_sel_hi:[1,0]
	v_pk_mul_f32 v[118:119], v[106:107], v[114:115] op_sel_hi:[1,0]
	v_pk_mul_f32 v[106:107], v[104:105], v[114:115] op_sel_hi:[1,0]
	v_cvt_pk_bf16_f32 v104, v108, v109
	v_cvt_pk_bf16_f32 v105, v110, v111
	v_cvt_pk_bf16_f32 v106, v106, v107
	v_cvt_pk_bf16_f32 v107, v118, v119
	global_store_dwordx4 v[112:113], v[104:107], off
	s_nop 7
	s_waitcnt vmcnt(7)
; __device__ __forceinline__ unsigned cvtpk(float lo, float hi) { f32x2v_ v = {lo, hi}; bf16x2v_ b = __builtin_convertvector(v, bf16x2v_); return __builtin_bit_cast(unsigned, b); }
; __device__ __forceinline__ float row_rs(const float* ssp, int row) { const unsigned long long v = ((const unsigned long long*)ssp)[row];
;     return __builtin_amdgcn_rsqf((float)v * (1.0f / 4294967296.0f) * (1.0f / 1024.0f) + RMS_EPS); }
;     __device__ __forceinline__ void operator()(const f32x4 (&acc)[2][2][4][2], const Unit& u, int wr, int wc, int fr, int fq) const {
;     ...
;             if (cbase < kbeg) {
; #pragma unroll
;                 for (int ai = 0; ai < 2; ++ai)
; #pragma unroll
;                     for (int m = 0; m < 4; ++m) { const int row = row0 + ai * HALF + m * 16; const float rs = ss ? row_rs(ss, row) : 1.0f;
;                         const f32x4 v0 = acc[ai][bj][m][0] * rs, v1 = acc[ai][bj][m][1] * rs;
;                         u32x4 w; w.x = cvtpk(v0[0], v0[1]); w.y = cvtpk(v0[2], v0[3]); w.z = cvtpk(v1[0], v1[1]); w.w = cvtpk(v1[2], v1[3]);
;                         *(u32x4*)(O + (size_t)row * ldc + c0) = w; }
	v_ffbh_u32_e32 v106, v187
	v_min_u32_e32 v106, 32, v106
	v_lshlrev_b64 v[104:105], v106, v[186:187]
	v_min_u32_e32 v104, 1, v104
	v_or_b32_e32 v104, v105, v104
	v_cvt_f32_u32_e32 v104, v104
	v_sub_u32_e32 v105, 32, v106
	v_lshlrev_b64 v[106:107], 12, v[128:129]
	v_lshl_add_u64 v[106:107], s[20:21], 0, v[106:107]
	v_ldexp_f32 v104, v104, v105
	v_mul_f32_e32 v104, 0x2f800000, v104
	v_fmamk_f32 v104, v104, 0x3a800000, v209
	v_rsq_f32_e32 v104, v104
	v_lshl_add_u64 v[106:107], v[106:107], 0, v[168:169]
	v_pk_mul_f32 v[102:103], v[102:103], v[104:105] op_sel_hi:[1,0]
	v_pk_mul_f32 v[100:101], v[100:101], v[104:105] op_sel_hi:[1,0]
	v_pk_mul_f32 v[108:109], v[98:99], v[104:105] op_sel_hi:[1,0]
	v_pk_mul_f32 v[98:99], v[96:97], v[104:105] op_sel_hi:[1,0]
	v_cvt_pk_bf16_f32 v96, v100, v101
	v_cvt_pk_bf16_f32 v97, v102, v103
	v_cvt_pk_bf16_f32 v98, v98, v99
	v_cvt_pk_bf16_f32 v99, v108, v109
	global_store_dwordx4 v[106:107], v[96:99], off
	s_nop 7
	s_waitcnt vmcnt(7)
	v_ffbh_u32_e32 v98, v189
	v_min_u32_e32 v98, 32, v98
	v_lshlrev_b64 v[96:97], v98, v[188:189]
	v_min_u32_e32 v96, 1, v96
	v_or_b32_e32 v96, v97, v96
	v_cvt_f32_u32_e32 v96, v96
	v_sub_u32_e32 v97, 32, v98
	v_add_co_u32_e32 v98, vcc, s84, v166
	v_ldexp_f32 v96, v96, v97
	v_mul_f32_e32 v96, 0x2f800000, v96
	v_fmamk_f32 v96, v96, 0x3a800000, v209
	v_rsq_f32_e32 v96, v96
	v_addc_co_u32_e32 v99, vcc, 0, v167, vcc
	v_pk_mul_f32 v[94:95], v[94:95], v[96:97] op_sel_hi:[1,0]
	v_pk_mul_f32 v[92:93], v[92:93], v[96:97] op_sel_hi:[1,0]
	v_pk_mul_f32 v[100:101], v[90:91], v[96:97] op_sel_hi:[1,0]
	v_pk_mul_f32 v[90:91], v[88:89], v[96:97] op_sel_hi:[1,0]
	v_cvt_pk_bf16_f32 v88, v92, v93
	v_cvt_pk_bf16_f32 v89, v94, v95
	v_cvt_pk_bf16_f32 v90, v90, v91
	v_cvt_pk_bf16_f32 v91, v100, v101
	global_store_dwordx4 v[98:99], v[88:91], off
	s_nop 7
	s_waitcnt vmcnt(7)
	v_ffbh_u32_e32 v90, v191
	v_min_u32_e32 v90, 32, v90
	v_lshlrev_b64 v[88:89], v90, v[190:191]
	v_min_u32_e32 v88, 1, v88
	v_or_b32_e32 v88, v89, v88
	v_cvt_f32_u32_e32 v88, v88
	v_sub_u32_e32 v89, 32, v90
	v_add_co_u32_e32 v90, vcc, s85, v166
	v_ldexp_f32 v88, v88, v89
	v_mul_f32_e32 v88, 0x2f800000, v88
	v_fmamk_f32 v88, v88, 0x3a800000, v209
	v_rsq_f32_e32 v88, v88
	v_addc_co_u32_e32 v91, vcc, 0, v167, vcc
	v_pk_mul_f32 v[86:87], v[86:87], v[88:89] op_sel_hi:[1,0]
	v_pk_mul_f32 v[84:85], v[84:85], v[88:89] op_sel_hi:[1,0]
	v_pk_mul_f32 v[92:93], v[82:83], v[88:89] op_sel_hi:[1,0]
	v_pk_mul_f32 v[82:83], v[80:81], v[88:89] op_sel_hi:[1,0]
	v_cvt_pk_bf16_f32 v80, v84, v85
	v_cvt_pk_bf16_f32 v81, v86, v87
	v_cvt_pk_bf16_f32 v82, v82, v83
	v_cvt_pk_bf16_f32 v83, v92, v93
	global_store_dwordx4 v[90:91], v[80:83], off
	s_nop 7
	s_waitcnt vmcnt(7)
	v_ffbh_u32_e32 v82, v193
	v_min_u32_e32 v82, 32, v82
	v_lshlrev_b64 v[80:81], v82, v[192:193]
	v_min_u32_e32 v80, 1, v80
	v_or_b32_e32 v80, v81, v80
	v_cvt_f32_u32_e32 v80, v80
	v_sub_u32_e32 v81, 32, v82
	v_add_co_u32_e32 v82, vcc, s86, v166
	v_ldexp_f32 v80, v80, v81
	v_mul_f32_e32 v80, 0x2f800000, v80
	v_fmamk_f32 v80, v80, 0x3a800000, v209
	v_rsq_f32_e32 v80, v80
	v_addc_co_u32_e32 v83, vcc, 0, v167, vcc
	v_pk_mul_f32 v[78:79], v[78:79], v[80:81] op_sel_hi:[1,0]
	v_pk_mul_f32 v[76:77], v[76:77], v[80:81] op_sel_hi:[1,0]
	v_pk_mul_f32 v[84:85], v[74:75], v[80:81] op_sel_hi:[1,0]
	v_pk_mul_f32 v[74:75], v[72:73], v[80:81] op_sel_hi:[1,0]
	v_cvt_pk_bf16_f32 v72, v76, v77
	v_cvt_pk_bf16_f32 v73, v78, v79
	v_cvt_pk_bf16_f32 v74, v74, v75
	v_cvt_pk_bf16_f32 v75, v84, v85
	global_store_dwordx4 v[82:83], v[72:75], off
	s_nop 7
	s_waitcnt vmcnt(7)
	v_ffbh_u32_e32 v74, v195
	v_min_u32_e32 v74, 32, v74
	v_lshlrev_b64 v[72:73], v74, v[194:195]
	v_min_u32_e32 v72, 1, v72
	v_or_b32_e32 v72, v73, v72
	v_cvt_f32_u32_e32 v72, v72
	v_sub_u32_e32 v73, 32, v74
	v_add_co_u32_e32 v74, vcc, 0xb0000, v166
	v_ldexp_f32 v72, v72, v73
	v_mul_f32_e32 v72, 0x2f800000, v72
	v_fmamk_f32 v72, v72, 0x3a800000, v209
	v_rsq_f32_e32 v72, v72
	v_addc_co_u32_e32 v75, vcc, 0, v167, vcc
	v_pk_mul_f32 v[70:71], v[70:71], v[72:73] op_sel_hi:[1,0]
	v_pk_mul_f32 v[68:69], v[68:69], v[72:73] op_sel_hi:[1,0]
	v_pk_mul_f32 v[76:77], v[66:67], v[72:73] op_sel_hi:[1,0]
	v_pk_mul_f32 v[66:67], v[64:65], v[72:73] op_sel_hi:[1,0]
	v_cvt_pk_bf16_f32 v64, v68, v69
	v_cvt_pk_bf16_f32 v65, v70, v71
	v_cvt_pk_bf16_f32 v66, v66, v67
	v_cvt_pk_bf16_f32 v67, v76, v77
	global_store_dwordx4 v[74:75], v[64:67], off
	s_nop 7
	s_or_b32 s49, s58, 0x80
	s_cmpk_lt_i32 s49, 0x400
	s_mov_b64 s[60:61], -1
	s_cbranch_scc1 .LBB0_1300

; __device__ __forceinline__ unsigned cvtpk(float lo, float hi) { f32x2v_ v = {lo, hi}; bf16x2v_ b = __builtin_convertvector(v, bf16x2v_); return __builtin_bit_cast(unsigned, b); }
; __device__ __forceinline__ float row_rs(const float* ssp, int row) { const unsigned long long v = ((const unsigned long long*)ssp)[row];
;     return __builtin_amdgcn_rsqf((float)v * (1.0f / 4294967296.0f) * (1.0f / 1024.0f) + RMS_EPS); }
;     __device__ __forceinline__ void operator()(const f32x4 (&acc)[2][2][4][2], const Unit& u, int wr, int wc, int fr, int fq) const {
;     ...
;             if (cbase < kbeg) {
; #pragma unroll
;                 for (int ai = 0; ai < 2; ++ai)
; #pragma unroll
;                     for (int m = 0; m < 4; ++m) { const int row = row0 + ai * HALF + m * 16; const float rs = ss ? row_rs(ss, row) : 1.0f;
;                         const f32x4 v0 = acc[ai][bj][m][0] * rs, v1 = acc[ai][bj][m][1] * rs;
;                         u32x4 w; w.x = cvtpk(v0[0], v0[1]); w.y = cvtpk(v0[2], v0[3]); w.z = cvtpk(v1[0], v1[1]); w.w = cvtpk(v1[2], v1[3]);
;                         *(u32x4*)(O + (size_t)row * ldc + c0) = w; }
.LBB0_1310:
	v_lshl_add_u64 v[64:65], v[160:161], 3, s[36:37]
	global_load_dwordx2 v[66:67], v[64:65], off
	v_mov_b32_e32 v76, v162
	v_ashrrev_i32_e32 v77, 31, v76
	v_lshl_add_u64 v[76:77], v[76:77], 3, s[36:37]
	global_load_dwordx2 v[76:77], v[76:77], off
	v_mov_b32_e32 v78, v130
	v_ashrrev_i32_e32 v79, 31, v78
	v_lshl_add_u64 v[78:79], v[78:79], 3, s[36:37]
	global_load_dwordx2 v[78:79], v[78:79], off
	v_mov_b32_e32 v80, v128
	v_ashrrev_i32_e32 v81, 31, v80
	v_lshl_add_u64 v[80:81], v[80:81], 3, s[36:37]
	global_load_dwordx2 v[80:81], v[80:81], off
	global_load_dwordx2 v[82:83], v[64:65], off offset:1024
	global_load_dwordx2 v[84:85], v[64:65], off offset:1152
	global_load_dwordx2 v[86:87], v[64:65], off offset:1280
	global_load_dwordx2 v[88:89], v[64:65], off offset:1408
	s_waitcnt lgkmcnt(0)
	v_lshlrev_b64 v[68:69], 12, v[160:161]
	s_ashr_i32 s59, s58, 31
	s_waitcnt vmcnt(7)
	v_ffbh_u32_e32 v70, v67
	v_min_u32_e32 v72, 32, v70
	v_lshlrev_b64 v[66:67], v72, v[66:67]
	v_min_u32_e32 v66, 1, v66
	v_or_b32_e32 v66, v67, v66
	v_cvt_f32_u32_e32 v73, v66
	v_lshl_add_u64 v[66:67], s[20:21], 0, v[68:69]
	v_sub_u32_e32 v68, 32, v72
	v_lshl_add_u64 v[70:71], v[162:163], 3, s[36:37]
	v_ldexp_f32 v68, v73, v68
	v_mul_f32_e32 v68, 0x2f800000, v68
	v_fmamk_f32 v68, v68, 0x3a800000, v209
	v_rsq_f32_e32 v68, v68
	v_lshl_add_u64 v[72:73], s[58:59], 0, v[142:143]
	v_lshlrev_b64 v[72:73], 1, v[72:73]
	v_lshl_add_u64 v[66:67], v[66:67], 0, v[72:73]
	v_pk_mul_f32 v[62:63], v[62:63], v[68:69] op_sel_hi:[1,0]
	v_pk_mul_f32 v[60:61], v[60:61], v[68:69] op_sel_hi:[1,0]
	v_pk_mul_f32 v[74:75], v[58:59], v[68:69] op_sel_hi:[1,0]
	v_pk_mul_f32 v[58:59], v[56:57], v[68:69] op_sel_hi:[1,0]
	v_cvt_pk_bf16_f32 v56, v60, v61
	v_cvt_pk_bf16_f32 v57, v62, v63
	v_cvt_pk_bf16_f32 v58, v58, v59
	v_cvt_pk_bf16_f32 v59, v74, v75
	global_store_dwordx4 v[66:67], v[56:59], off offset:256
	s_nop 7
	v_lshl_add_u64 v[60:61], v[130:131], 3, s[36:37]
	s_waitcnt vmcnt(7)
	v_ffbh_u32_e32 v58, v77
	v_min_u32_e32 v58, 32, v58
	v_lshlrev_b64 v[56:57], v58, v[76:77]
	v_min_u32_e32 v56, 1, v56
	v_or_b32_e32 v56, v57, v56
	v_cvt_f32_u32_e32 v59, v56
	v_sub_u32_e32 v58, 32, v58
	v_lshlrev_b64 v[56:57], 12, v[162:163]
	v_lshl_add_u64 v[56:57], s[20:21], 0, v[56:57]
	v_ldexp_f32 v58, v59, v58
	v_mul_f32_e32 v58, 0x2f800000, v58
	v_fmamk_f32 v58, v58, 0x3a800000, v209
	v_rsq_f32_e32 v58, v58
	v_lshl_add_u64 v[56:57], v[56:57], 0, v[72:73]
	v_pk_mul_f32 v[54:55], v[54:55], v[58:59] op_sel_hi:[1,0]
	v_pk_mul_f32 v[52:53], v[52:53], v[58:59] op_sel_hi:[1,0]
	v_pk_mul_f32 v[62:63], v[50:51], v[58:59] op_sel_hi:[1,0]
	v_pk_mul_f32 v[50:51], v[48:49], v[58:59] op_sel_hi:[1,0]
	v_cvt_pk_bf16_f32 v48, v52, v53
	v_cvt_pk_bf16_f32 v49, v54, v55
	v_cvt_pk_bf16_f32 v50, v50, v51
	v_cvt_pk_bf16_f32 v51, v62, v63
	global_store_dwordx4 v[56:57], v[48:51], off offset:256
	s_nop 7
	v_lshl_add_u64 v[52:53], v[128:129], 3, s[36:37]
	s_waitcnt vmcnt(7)
	v_ffbh_u32_e32 v50, v79
	v_min_u32_e32 v50, 32, v50
	v_lshlrev_b64 v[48:49], v50, v[78:79]
	v_min_u32_e32 v48, 1, v48
	v_or_b32_e32 v48, v49, v48
	v_cvt_f32_u32_e32 v51, v48
	v_sub_u32_e32 v50, 32, v50
	v_lshlrev_b64 v[48:49], 12, v[130:131]
	v_lshl_add_u64 v[48:49], s[20:21], 0, v[48:49]
	v_ldexp_f32 v50, v51, v50
	v_mul_f32_e32 v50, 0x2f800000, v50
	v_fmamk_f32 v50, v50, 0x3a800000, v209
	v_rsq_f32_e32 v50, v50
	v_lshl_add_u64 v[48:49], v[48:49], 0, v[72:73]
	v_pk_mul_f32 v[46:47], v[46:47], v[50:51] op_sel_hi:[1,0]
	v_pk_mul_f32 v[44:45], v[44:45], v[50:51] op_sel_hi:[1,0]
	v_pk_mul_f32 v[54:55], v[42:43], v[50:51] op_sel_hi:[1,0]
	v_pk_mul_f32 v[42:43], v[40:41], v[50:51] op_sel_hi:[1,0]
	v_cvt_pk_bf16_f32 v40, v44, v45
	v_cvt_pk_bf16_f32 v41, v46, v47
	v_cvt_pk_bf16_f32 v42, v42, v43
	v_cvt_pk_bf16_f32 v43, v54, v55
	global_store_dwordx4 v[48:49], v[40:43], off offset:256
	s_nop 7
	s_waitcnt vmcnt(7)
; __device__ __forceinline__ unsigned cvtpk(float lo, float hi) { f32x2v_ v = {lo, hi}; bf16x2v_ b = __builtin_convertvector(v, bf16x2v_); return __builtin_bit_cast(unsigned, b); }
; __device__ __forceinline__ float row_rs(const float* ssp, int row) { const unsigned long long v = ((const unsigned long long*)ssp)[row];
;     return __builtin_amdgcn_rsqf((float)v * (1.0f / 4294967296.0f) * (1.0f / 1024.0f) + RMS_EPS); }
;     __device__ __forceinline__ void operator()(const f32x4 (&acc)[2][2][4][2], const Unit& u, int wr, int wc, int fr, int fq) const {
;     ...
;             if (cbase < kbeg) {
; #pragma unroll
;                 for (int ai = 0; ai < 2; ++ai)
; #pragma unroll
;                     for (int m = 0; m < 4; ++m) { const int row = row0 + ai * HALF + m * 16; const float rs = ss ? row_rs(ss, row) : 1.0f;
;                         const f32x4 v0 = acc[ai][bj][m][0] * rs, v1 = acc[ai][bj][m][1] * rs;
;                         u32x4 w; w.x = cvtpk(v0[0], v0[1]); w.y = cvtpk(v0[2], v0[3]); w.z = cvtpk(v1[0], v1[1]); w.w = cvtpk(v1[2], v1[3]);
;                         *(u32x4*)(O + (size_t)row * ldc + c0) = w; }
	v_ffbh_u32_e32 v42, v81
	v_min_u32_e32 v42, 32, v42
	v_lshlrev_b64 v[40:41], v42, v[80:81]
	v_min_u32_e32 v40, 1, v40
	v_or_b32_e32 v40, v41, v40
	v_cvt_f32_u32_e32 v40, v40
	v_sub_u32_e32 v41, 32, v42
	v_lshlrev_b64 v[42:43], 12, v[128:129]
	v_lshl_add_u64 v[42:43], s[20:21], 0, v[42:43]
	v_ldexp_f32 v40, v40, v41
	v_mul_f32_e32 v40, 0x2f800000, v40
	v_fmamk_f32 v40, v40, 0x3a800000, v209
	v_rsq_f32_e32 v40, v40
	v_lshl_add_u64 v[42:43], v[42:43], 0, v[72:73]
	v_pk_mul_f32 v[38:39], v[38:39], v[40:41] op_sel_hi:[1,0]
	v_pk_mul_f32 v[36:37], v[36:37], v[40:41] op_sel_hi:[1,0]
	v_pk_mul_f32 v[44:45], v[34:35], v[40:41] op_sel_hi:[1,0]
	v_pk_mul_f32 v[34:35], v[32:33], v[40:41] op_sel_hi:[1,0]
	v_cvt_pk_bf16_f32 v32, v36, v37
	v_cvt_pk_bf16_f32 v33, v38, v39
	v_cvt_pk_bf16_f32 v34, v34, v35
	v_cvt_pk_bf16_f32 v35, v44, v45
	global_store_dwordx4 v[42:43], v[32:35], off offset:256
	s_nop 7
	s_waitcnt vmcnt(7)
	v_ffbh_u32_e32 v34, v83
	v_min_u32_e32 v34, 32, v34
	v_lshlrev_b64 v[32:33], v34, v[82:83]
	v_min_u32_e32 v32, 1, v32
	v_or_b32_e32 v32, v33, v32
	v_cvt_f32_u32_e32 v32, v32
	v_sub_u32_e32 v33, 32, v34
	v_add_co_u32_e32 v34, vcc, s84, v66
	v_ldexp_f32 v32, v32, v33
	v_mul_f32_e32 v32, 0x2f800000, v32
	v_fmamk_f32 v32, v32, 0x3a800000, v209
	v_rsq_f32_e32 v32, v32
	v_addc_co_u32_e32 v35, vcc, 0, v67, vcc
	v_pk_mul_f32 v[30:31], v[30:31], v[32:33] op_sel_hi:[1,0]
	v_pk_mul_f32 v[28:29], v[28:29], v[32:33] op_sel_hi:[1,0]
	v_pk_mul_f32 v[36:37], v[26:27], v[32:33] op_sel_hi:[1,0]
	v_pk_mul_f32 v[26:27], v[24:25], v[32:33] op_sel_hi:[1,0]
	v_cvt_pk_bf16_f32 v24, v28, v29
	v_cvt_pk_bf16_f32 v25, v30, v31
	v_cvt_pk_bf16_f32 v26, v26, v27
	v_cvt_pk_bf16_f32 v27, v36, v37
	global_store_dwordx4 v[34:35], v[24:27], off offset:256
	s_nop 7
	s_waitcnt vmcnt(7)
	v_ffbh_u32_e32 v26, v85
	v_min_u32_e32 v26, 32, v26
	v_lshlrev_b64 v[24:25], v26, v[84:85]
	v_min_u32_e32 v24, 1, v24
	v_or_b32_e32 v24, v25, v24
	v_cvt_f32_u32_e32 v24, v24
	v_sub_u32_e32 v25, 32, v26
	v_add_co_u32_e32 v26, vcc, s85, v66
	v_ldexp_f32 v24, v24, v25
	v_mul_f32_e32 v24, 0x2f800000, v24
	v_fmamk_f32 v24, v24, 0x3a800000, v209
	v_rsq_f32_e32 v24, v24
	v_addc_co_u32_e32 v27, vcc, 0, v67, vcc
	v_pk_mul_f32 v[22:23], v[22:23], v[24:25] op_sel_hi:[1,0]
	v_pk_mul_f32 v[20:21], v[20:21], v[24:25] op_sel_hi:[1,0]
	v_pk_mul_f32 v[28:29], v[18:19], v[24:25] op_sel_hi:[1,0]
	v_pk_mul_f32 v[18:19], v[16:17], v[24:25] op_sel_hi:[1,0]
	v_cvt_pk_bf16_f32 v16, v20, v21
	v_cvt_pk_bf16_f32 v17, v22, v23
	v_cvt_pk_bf16_f32 v18, v18, v19
	v_cvt_pk_bf16_f32 v19, v28, v29
	global_store_dwordx4 v[26:27], v[16:19], off offset:256
	s_nop 7
	s_waitcnt vmcnt(7)
	v_ffbh_u32_e32 v18, v87
	v_min_u32_e32 v18, 32, v18
	v_lshlrev_b64 v[16:17], v18, v[86:87]
	v_min_u32_e32 v16, 1, v16
	v_or_b32_e32 v16, v17, v16
	v_cvt_f32_u32_e32 v16, v16
	v_sub_u32_e32 v17, 32, v18
	v_add_co_u32_e32 v18, vcc, s86, v66
	v_ldexp_f32 v16, v16, v17
	v_mul_f32_e32 v16, 0x2f800000, v16
	v_fmamk_f32 v16, v16, 0x3a800000, v209
	v_rsq_f32_e32 v16, v16
	v_addc_co_u32_e32 v19, vcc, 0, v67, vcc
	v_pk_mul_f32 v[14:15], v[14:15], v[16:17] op_sel_hi:[1,0]
	v_pk_mul_f32 v[12:13], v[12:13], v[16:17] op_sel_hi:[1,0]
	v_pk_mul_f32 v[20:21], v[10:11], v[16:17] op_sel_hi:[1,0]
	v_pk_mul_f32 v[10:11], v[8:9], v[16:17] op_sel_hi:[1,0]
	v_cvt_pk_bf16_f32 v8, v12, v13
	v_cvt_pk_bf16_f32 v9, v14, v15
	v_cvt_pk_bf16_f32 v10, v10, v11
	v_cvt_pk_bf16_f32 v11, v20, v21
	global_store_dwordx4 v[18:19], v[8:11], off offset:256
	s_nop 7
	s_waitcnt vmcnt(7)
	v_ffbh_u32_e32 v10, v89
	v_min_u32_e32 v10, 32, v10
	v_lshlrev_b64 v[8:9], v10, v[88:89]
	v_min_u32_e32 v8, 1, v8
	v_or_b32_e32 v8, v9, v8
	v_cvt_f32_u32_e32 v8, v8
	v_sub_u32_e32 v9, 32, v10
	v_add_co_u32_e32 v10, vcc, 0xb0000, v66
	v_ldexp_f32 v8, v8, v9
	v_mul_f32_e32 v8, 0x2f800000, v8
	v_fmamk_f32 v8, v8, 0x3a800000, v209
	v_rsq_f32_e32 v8, v8
	v_addc_co_u32_e32 v11, vcc, 0, v67, vcc
	v_pk_mul_f32 v[6:7], v[6:7], v[8:9] op_sel_hi:[1,0]
	v_pk_mul_f32 v[4:5], v[4:5], v[8:9] op_sel_hi:[1,0]
	v_pk_mul_f32 v[12:13], v[2:3], v[8:9] op_sel_hi:[1,0]
	v_pk_mul_f32 v[2:3], v[0:1], v[8:9] op_sel_hi:[1,0]
	v_cvt_pk_bf16_f32 v0, v4, v5
	v_cvt_pk_bf16_f32 v1, v6, v7
	v_cvt_pk_bf16_f32 v2, v2, v3
	v_cvt_pk_bf16_f32 v3, v12, v13
	global_store_dwordx4 v[10:11], v[0:3], off offset:256
	s_nop 7
	s_andn2_b64 vcc, exec, s[12:13]
	s_mov_b64 s[12:13], -1
	s_cbranch_vccnz .LBB0_1279
